# attention K-tile LDS XOR swizzle widened from (row&7) to (row&15): removes 2-way bank conflict of the QK^T ds_read_b128, on top of v12
# baseline (speedup 1.0000x reference)
; __device__ __forceinline__ int v_st(int k, int c) { const int kk = (k & ~0xC) | ((k & 4) << 1) | ((k & 8) >> 1); return ((kk >> 3) * 4 + (c >> 5)) * 512 + ((kk & 7) * 32 + (c & 31)) * 2; }
; __device__ __forceinline__ int v_rd_base(int lane) { return ((lane & 3) << 3) | (((lane >> 2) & 3) << 6) | (((lane >> 4) & 1) << 5) | (((lane >> 5) & 1) << 8); }
; __device__ __forceinline__ void attn_dense_body(const bf16* __restrict__ Qb, const bf16* __restrict__ Kh, const bf16* __restrict__ Vh,
;                                                 bf16* __restrict__ Ob, int seq, char* lds, const float negb) {
;   const int tid = threadIdx.x, wid = tid >> 6, lane = tid & 63, r32 = lane & 31, hi = lane >> 5;
;   bf16* V_lds = (bf16*)lds; bf16* K_lds = (bf16*)(lds + 2 * SHM_V);
;   float* ws = (float*)(lds + 2 * SHM_V + 2 * SHM_K) + wid * 64; float* li_l = ws;
;   float l_reg = 0; f32x16 o[4] = {}; bf16x8 qr[8];
;   const bf16* Qw = Qb + (long)(wid * QBLK + r32) * LDQ + hi * 8;
; #pragma unroll
;   for (int d0 = 0; d0 < 8; ++d0) qr[d0] = ld8(Qw + d0 * 16);
;   const int sr = tid >> 4, sc = (tid & 15) * 8, vst0 = v_st(sr, sc), vst1 = v_st(32 + sr, sc);
;   const int vb0 = (int)(uintptr_t)V_lds + v_rd_base(lane);
;   struct { bf16x8 vs0, vs1, ks0, ks1; } sr_[1];
;   const unsigned so0 = (unsigned)(sr * LDK + sc);
.LBB0_279:
	s_cmp_lt_i32 s74, 7
	s_cselect_b64 s[0:1], -1, 0
	s_cmp_gt_i32 s75, 6
	s_cselect_b64 s[4:5], -1, 0
	s_and_b64 s[84:85], s[0:1], s[4:5]
	v_cndmask_b32_e64 v0, 0, 1, s[84:85]
	v_cmp_ne_u32_e64 s[92:93], 1, v0
	s_andn2_b64 vcc, exec, s[84:85]
	v_mbcnt_lo_u32_b32 v254, -1, 0
	s_cbranch_vccnz .LBB0_289
	v_lshlrev_b32_e32 v0, 2, v144
	s_waitcnt vmcnt(0)
	s_barrier
	global_load_dword v1, v0, s[50:51] offset:256
	global_load_dword v2, v0, s[50:51]
	global_load_dword v3, v0, s[52:53] offset:256
	s_nop 0
	global_load_dword v0, v0, s[52:53]
	v_mbcnt_hi_u32_b32 v4, -1, v254
	v_and_b32_e32 v5, 64, v4
	v_xor_b32_e32 v6, 1, v4
	v_add_u32_e32 v5, 64, v5
	v_cmp_lt_i32_e32 vcc, v6, v5
	v_xor_b32_e32 v7, 2, v4
	v_xor_b32_e32 v8, 4, v4
	v_cndmask_b32_e32 v6, v4, v6, vcc
	v_lshlrev_b32_e32 v6, 2, v6
	v_cmp_lt_i32_e32 vcc, v7, v5
	v_xor_b32_e32 v9, 8, v4
	v_xor_b32_e32 v10, 16, v4
	v_xor_b32_e32 v11, 32, v4
	s_cmp_lt_i32 s79, 1
	s_mov_b32 s9, 0
	s_waitcnt vmcnt(3)
	v_max_f32_e64 v1, |v1|, |v1|
	s_waitcnt vmcnt(2)
	v_max_f32_e64 v2, |v2|, |v2|
	s_waitcnt vmcnt(1)
	v_max_f32_e64 v3, |v3|, |v3|
	s_waitcnt vmcnt(0)
	v_max_f32_e64 v0, |v0|, |v0|
	v_max_f32_e32 v1, v2, v1
	v_max_f32_e32 v0, v0, v3
	ds_bpermute_b32 v2, v6, v1
	ds_bpermute_b32 v3, v6, v0
	v_cndmask_b32_e32 v6, v4, v7, vcc
	v_lshlrev_b32_e32 v6, 2, v6
	v_cmp_lt_i32_e32 vcc, v8, v5
	s_waitcnt lgkmcnt(1)
	v_max_f32_e32 v2, v2, v2
	s_waitcnt lgkmcnt(0)
	v_max_f32_e32 v3, v3, v3
	v_max_f32_e32 v1, v1, v2
	v_max_f32_e32 v0, v0, v3
	ds_bpermute_b32 v2, v6, v1
	ds_bpermute_b32 v3, v6, v0
	v_cndmask_b32_e32 v6, v4, v8, vcc
	v_lshlrev_b32_e32 v6, 2, v6
	v_cmp_lt_i32_e32 vcc, v9, v5
	s_waitcnt lgkmcnt(1)
	v_max_f32_e32 v2, v2, v2
	s_waitcnt lgkmcnt(0)
	v_max_f32_e32 v3, v3, v3
	v_max_f32_e32 v1, v1, v2
	v_max_f32_e32 v0, v0, v3
	ds_bpermute_b32 v2, v6, v1
	ds_bpermute_b32 v3, v6, v0
	v_cndmask_b32_e32 v6, v4, v9, vcc
	v_lshlrev_b32_e32 v6, 2, v6
	v_cmp_lt_i32_e32 vcc, v10, v5
	s_waitcnt lgkmcnt(1)
	v_max_f32_e32 v2, v2, v2
	s_waitcnt lgkmcnt(0)
	v_max_f32_e32 v3, v3, v3
	v_max_f32_e32 v1, v1, v2
	v_max_f32_e32 v0, v0, v3
	ds_bpermute_b32 v2, v6, v1
	ds_bpermute_b32 v3, v6, v0
	v_cndmask_b32_e32 v6, v4, v10, vcc
	v_lshlrev_b32_e32 v6, 2, v6
	v_cmp_lt_i32_e32 vcc, v11, v5
	s_waitcnt lgkmcnt(1)
	v_max_f32_e32 v2, v2, v2
	s_waitcnt lgkmcnt(0)
	v_max_f32_e32 v3, v3, v3
	v_max_f32_e32 v1, v1, v2
	v_max_f32_e32 v2, v0, v3
	ds_bpermute_b32 v0, v6, v1
	ds_bpermute_b32 v3, v6, v2
	v_cndmask_b32_e32 v4, v4, v11, vcc
	v_lshlrev_b32_e32 v4, 2, v4
	s_waitcnt lgkmcnt(1)
	v_max_f32_e32 v0, v0, v0
	s_waitcnt lgkmcnt(0)
	v_max_f32_e32 v3, v3, v3
	v_max_f32_e32 v0, v1, v0
	v_max_f32_e32 v2, v2, v3
	ds_bpermute_b32 v1, v4, v0
	ds_bpermute_b32 v3, v4, v2
	s_cbranch_scc1 .LBB0_289
	s_waitcnt lgkmcnt(0)
	v_max_f32_e32 v3, v3, v3
	v_max_f32_e32 v2, v2, v2
	v_max_f32_e32 v2, v2, v3
	v_and_b32_e32 v3, 0x3c0, v145
	s_add_i32 s0, 0, 0x10000
	v_lshl_add_u32 v180, v3, 2, s0
	v_lshrrev_b32_e32 v3, 4, v145
	v_and_b32_e32 v8, 48, v3
	v_lshlrev_b32_e32 v6, 3, v145
	v_and_or_b32 v8, v187, 8, v8
	v_and_b32_e32 v7, 0x78, v6
	v_lshrrev_b32_e32 v9, 5, v145
	v_lshrrev_b32_e32 v8, 1, v8
	v_bfe_u32 v10, v6, 5, 2
	v_bfe_u32 v11, v145, 4, 2
	v_or_b32_e32 v8, v8, v10
	v_and_or_b32 v9, v9, 4, v11
	v_lshlrev_b32_e32 v11, 1, v7
	v_lshlrev_b32_e32 v8, 9, v8
	v_lshlrev_b32_e32 v9, 6, v9
	v_and_b32_e32 v12, 48, v11
	v_or3_b32 v14, v8, v9, v12
	v_add_u32_e32 v8, 32, v3
	v_and_b32_e32 v13, 0x70, v8
	v_lshlrev_b32_e32 v15, 1, v8
	v_and_or_b32 v13, v15, 8, v13
	v_lshrrev_b32_e32 v13, 1, v13
	v_or_b32_e32 v10, v13, v10
	v_max_f32_e32 v1, v1, v1
	v_max_f32_e32 v0, v0, v0
	v_lshlrev_b32_e32 v10, 9, v10
	v_max_f32_e32 v0, v0, v1
	v_or3_b32 v9, v10, v9, v12
	v_lshlrev_b32_e32 v12, 1, v145
	v_mul_f32_e32 v0, 0xc1853333, v0
	v_and_b32_e32 v10, 0xc0, v186
	v_and_b32_e32 v12, 32, v12
	v_and_b32_e32 v6, 0x118, v6
	v_mul_f32_e32 v0, v2, v0
	v_lshrrev_b32_e32 v1, 5, v144
	v_or3_b32 v10, v12, v10, v6
	v_mul_u32_u24_e32 v6, 0x600, v3
	v_max_f32_e32 v146, 0xc2700000, v0
	v_and_b32_e32 v0, 31, v145
	v_or_b32_e32 v6, v6, v7
	v_lshlrev_b32_e32 v3, 8, v3
	v_and_b32_e32 v7, 0xf0, v145
	v_lshlrev_b32_e32 v8, 8, v8
	v_lshlrev_b32_e32 v190, 4, v1
	v_bitop3_b32 v3, v11, v3, v7 bitop3:0xde
	v_bitop3_b32 v7, v11, v8, v7 bitop3:0xde
	v_lshlrev_b32_e32 v8, 8, v0
	v_and_b32_e32 v11, 0xf0, v186
	v_or_b32_e32 v12, 32, v190
	v_bitop3_b32 v16, v12, v8, v11 bitop3:0xde
	v_or_b32_e32 v12, 64, v190
	v_bitop3_b32 v17, v12, v8, v11 bitop3:0xde
	v_or_b32_e32 v12, 0x60, v190
	v_bitop3_b32 v18, v12, v8, v11 bitop3:0xde
	v_or_b32_e32 v12, 0x80, v190
	v_lshrrev_b32_e32 v2, 1, v145
	s_cmp_lg_u32 0, -1
	v_bitop3_b32 v19, v12, v8, v11 bitop3:0xde
	v_or_b32_e32 v12, 0xa0, v190
	v_and_b32_e32 v5, 0x1e0, v2
	s_cselect_b32 s0, 0, 0
	v_bitop3_b32 v20, v12, v8, v11 bitop3:0xde
	v_or_b32_e32 v12, 0xc0, v190
	v_or_b32_e32 v2, v5, v0
	v_mov_b32_e32 v149, 0
	v_add_u32_e32 v181, s0, v10
	v_bitop3_b32 v21, v12, v8, v11 bitop3:0xde
	v_or_b32_e32 v12, 0xe0, v190
	s_addk_i32 s0, 0x4000
	v_lshlrev_b32_e32 v148, 1, v6
	v_mul_u32_u24_e32 v2, 0x600, v2
	v_lshlrev_b32_e32 v4, 3, v1
	v_bitop3_b32 v15, v190, v8, v11 bitop3:0xde
	v_bitop3_b32 v11, v12, v8, v11 bitop3:0xde
	v_add_u32_e32 v191, s0, v10
	v_lshlrev_b32_e32 v8, 11, v5
	v_lshlrev_b32_e32 v10, 13, v1
	v_lshl_add_u64 v[12:13], s[72:73], 0, v[148:149]
	s_mov_b64 s[0:1], 0x14078a00
	v_mov_b32_e32 v147, v146
	v_mov_b32_e32 v150, v146
	v_mov_b32_e32 v151, v146
	v_mov_b32_e32 v152, v146
	v_mov_b32_e32 v153, v146
	v_mov_b32_e32 v154, v146
	v_mov_b32_e32 v155, v146
	v_mov_b32_e32 v156, v146
	v_mov_b32_e32 v157, v146
	v_mov_b32_e32 v158, v146
	v_mov_b32_e32 v159, v146
	v_mov_b32_e32 v160, v146
	v_mov_b32_e32 v161, v146
	v_mov_b32_e32 v162, v146
	v_mov_b32_e32 v163, v146
	v_cmp_gt_u32_e64 s[4:5], 32, v144
	v_lshl_add_u32 v192, v0, 2, v180
	v_add_u32_e32 v193, 0x48000, v6
	v_lshl_add_u64 v[164:165], v[12:13], 0, s[0:1]
	v_lshlrev_b32_e32 v166, 1, v2
	v_lshlrev_b32_e32 v168, 1, v4
	v_lshlrev_b32_e32 v170, 1, v6
	v_lshlrev_b32_e32 v172, 1, v8
	v_lshlrev_b32_e32 v174, 1, v10
	v_lshlrev_b32_e32 v176, 1, v0
	s_mov_b32 s0, 0x9000
	s_mov_b64 s[10:11], 0xa000
	s_mov_b64 s[12:13], 0xb000
	s_mov_b32 s1, 0xb000
	s_mov_b64 s[38:39], 0x10000
	s_mov_b64 s[40:41], 0x11000
	s_mov_b32 s3, 0x11000
	s_mov_b64 s[42:43], 0x12000
	s_mov_b64 s[44:45], 0x13000
	s_mov_b32 s28, 0x13000
	s_mov_b64 s[46:47], 0x18000
	s_mov_b64 s[48:49], 0x19000
	s_mov_b32 s29, 0x19000
	s_mov_b64 s[58:59], 0x1a000
	s_mov_b64 s[60:61], 0x1b000
	s_mov_b32 s34, 0x1b000
	v_add_u32_e32 v194, 0, v14
	v_add_u32_e32 v195, 0, v9
	v_add_u32_e32 v196, 0, v3
	v_add_u32_e32 v197, 0, v7
	v_add_u32_e32 v198, 0, v15
	v_add_u32_e32 v199, 0, v16
	v_add_u32_e32 v200, 0, v17
	v_add_u32_e32 v201, 0, v18
	v_add_u32_e32 v202, 0, v19
	v_add_u32_e32 v203, 0, v20
	v_add_u32_e32 v204, 0, v21
	v_add_u32_e32 v205, 0, v11
	s_mov_b32 s35, 0
	s_branch .LBB0_284

; __device__ __forceinline__ int v_st(int k, int c) { const int kk = (k & ~0xC) | ((k & 4) << 1) | ((k & 8) >> 1); return ((kk >> 3) * 4 + (c >> 5)) * 512 + ((kk & 7) * 32 + (c & 31)) * 2; }
; __device__ __forceinline__ int v_rd_base(int lane) { return ((lane & 3) << 3) | (((lane >> 2) & 3) << 6) | (((lane >> 4) & 1) << 5) | (((lane >> 5) & 1) << 8); }
; __device__ __forceinline__ void attn_dense_body(const bf16* __restrict__ Qb, const bf16* __restrict__ Kh, const bf16* __restrict__ Vh,
;                                                 bf16* __restrict__ Ob, int seq, char* lds, const float negb) {
;   const int tid = threadIdx.x, wid = tid >> 6, lane = tid & 63, r32 = lane & 31, hi = lane >> 5;
;   bf16* V_lds = (bf16*)lds; bf16* K_lds = (bf16*)(lds + 2 * SHM_V);
;   float* ws = (float*)(lds + 2 * SHM_V + 2 * SHM_K) + wid * 64; float* li_l = ws;
;   float l_reg = 0; f32x16 o[4] = {}; bf16x8 qr[8];
;   const bf16* Qw = Qb + (long)(wid * QBLK + r32) * LDQ + hi * 8;
; #pragma unroll
;   for (int d0 = 0; d0 < 8; ++d0) qr[d0] = ld8(Qw + d0 * 16);
;   const int sr = tid >> 4, sc = (tid & 15) * 8, vst0 = v_st(sr, sc), vst1 = v_st(32 + sr, sc);
;   const int vb0 = (int)(uintptr_t)V_lds + v_rd_base(lane);
;   struct { bf16x8 vs0, vs1, ks0, ks1; } sr_[1];
;   const unsigned so0 = (unsigned)(sr * LDK + sc);
.LBB0_509:
	s_and_b64 vcc, exec, s[92:93]
	s_cbranch_vccnz .LBB0_520
	v_lshlrev_b32_e32 v0, 2, v144
	s_waitcnt vmcnt(0) lgkmcnt(0)
	s_barrier
	global_load_dword v1, v0, s[50:51] offset:256
	global_load_dword v2, v0, s[50:51]
	global_load_dword v3, v0, s[52:53] offset:256
	global_load_dword v4, v0, s[52:53]
	v_mbcnt_hi_u32_b32 v0, -1, v254
	v_and_b32_e32 v5, 64, v0
	v_xor_b32_e32 v6, 1, v0
	v_add_u32_e32 v5, 64, v5
	v_cmp_lt_i32_e32 vcc, v6, v5
	v_xor_b32_e32 v7, 2, v0
	v_xor_b32_e32 v8, 4, v0
	v_cndmask_b32_e32 v6, v0, v6, vcc
	v_lshlrev_b32_e32 v6, 2, v6
	v_cmp_lt_i32_e32 vcc, v7, v5
	v_xor_b32_e32 v9, 8, v0
	v_xor_b32_e32 v10, 16, v0
	v_xor_b32_e32 v11, 32, v0
	v_readlane_b32 s0, v255, 11
	s_cmp_ge_i32 s79, s0
	s_mov_b32 s5, 0
	s_waitcnt vmcnt(3)
	v_max_f32_e64 v1, |v1|, |v1|
	s_waitcnt vmcnt(2)
	v_max_f32_e64 v2, |v2|, |v2|
	s_waitcnt vmcnt(1)
	v_max_f32_e64 v3, |v3|, |v3|
	s_waitcnt vmcnt(0)
	v_max_f32_e64 v4, |v4|, |v4|
	v_max_f32_e32 v1, v2, v1
	v_max_f32_e32 v2, v4, v3
	ds_bpermute_b32 v3, v6, v1
	ds_bpermute_b32 v4, v6, v2
	v_cndmask_b32_e32 v6, v0, v7, vcc
	v_lshlrev_b32_e32 v6, 2, v6
	v_cmp_lt_i32_e32 vcc, v8, v5
	s_waitcnt lgkmcnt(1)
	v_max_f32_e32 v3, v3, v3
	s_waitcnt lgkmcnt(0)
	v_max_f32_e32 v4, v4, v4
	v_max_f32_e32 v1, v1, v3
	v_max_f32_e32 v2, v2, v4
	ds_bpermute_b32 v3, v6, v1
	ds_bpermute_b32 v4, v6, v2
	v_cndmask_b32_e32 v6, v0, v8, vcc
	v_lshlrev_b32_e32 v6, 2, v6
	v_cmp_lt_i32_e32 vcc, v9, v5
	s_waitcnt lgkmcnt(1)
	v_max_f32_e32 v3, v3, v3
	s_waitcnt lgkmcnt(0)
	v_max_f32_e32 v4, v4, v4
	v_max_f32_e32 v1, v1, v3
	v_max_f32_e32 v2, v2, v4
	ds_bpermute_b32 v3, v6, v1
	ds_bpermute_b32 v4, v6, v2
	v_cndmask_b32_e32 v6, v0, v9, vcc
	v_lshlrev_b32_e32 v6, 2, v6
	v_cmp_lt_i32_e32 vcc, v10, v5
	s_waitcnt lgkmcnt(1)
	v_max_f32_e32 v3, v3, v3
	s_waitcnt lgkmcnt(0)
	v_max_f32_e32 v4, v4, v4
	v_max_f32_e32 v1, v1, v3
	v_max_f32_e32 v2, v2, v4
	ds_bpermute_b32 v3, v6, v1
	ds_bpermute_b32 v4, v6, v2
	v_cndmask_b32_e32 v6, v0, v10, vcc
	v_lshlrev_b32_e32 v6, 2, v6
	v_cmp_lt_i32_e32 vcc, v11, v5
	s_waitcnt lgkmcnt(1)
	v_max_f32_e32 v3, v3, v3
	s_waitcnt lgkmcnt(0)
	v_max_f32_e32 v4, v4, v4
	v_max_f32_e32 v1, v1, v3
	v_max_f32_e32 v2, v2, v4
	ds_bpermute_b32 v3, v6, v1
	ds_bpermute_b32 v4, v6, v2
	v_cndmask_b32_e32 v0, v0, v11, vcc
	v_lshlrev_b32_e32 v5, 2, v0
	s_waitcnt lgkmcnt(1)
	v_max_f32_e32 v0, v3, v3
	s_waitcnt lgkmcnt(0)
	v_max_f32_e32 v3, v4, v4
	v_max_f32_e32 v0, v1, v0
	v_max_f32_e32 v2, v2, v3
	ds_bpermute_b32 v1, v5, v0
	ds_bpermute_b32 v3, v5, v2
	s_cbranch_scc1 .LBB0_520
	s_waitcnt lgkmcnt(0)
	v_max_f32_e32 v3, v3, v3
	v_max_f32_e32 v2, v2, v2
	v_max_f32_e32 v2, v2, v3
	v_and_b32_e32 v3, 0x3c0, v145
	s_add_i32 s0, 0, 0x10000
	v_lshl_add_u32 v180, v3, 2, s0
	v_lshrrev_b32_e32 v3, 4, v145
	v_and_b32_e32 v8, 48, v3
	v_lshlrev_b32_e32 v6, 3, v145
	v_and_or_b32 v8, v187, 8, v8
	v_and_b32_e32 v7, 0x78, v6
	v_lshrrev_b32_e32 v9, 5, v145
	v_lshrrev_b32_e32 v8, 1, v8
	v_bfe_u32 v10, v6, 5, 2
	v_bfe_u32 v11, v145, 4, 2
	v_or_b32_e32 v8, v8, v10
	v_and_or_b32 v9, v9, 4, v11
	v_lshlrev_b32_e32 v11, 1, v7
	v_lshlrev_b32_e32 v8, 9, v8
	v_lshlrev_b32_e32 v9, 6, v9
	v_and_b32_e32 v12, 48, v11
	v_or3_b32 v14, v8, v9, v12
	v_add_u32_e32 v8, 32, v3
	v_and_b32_e32 v13, 0x70, v8
	v_lshlrev_b32_e32 v15, 1, v8
	v_and_or_b32 v13, v15, 8, v13
	v_lshrrev_b32_e32 v13, 1, v13
	v_or_b32_e32 v10, v13, v10
	v_max_f32_e32 v1, v1, v1
	v_max_f32_e32 v0, v0, v0
	v_lshlrev_b32_e32 v10, 9, v10
	v_max_f32_e32 v0, v0, v1
	v_or3_b32 v9, v10, v9, v12
	v_lshlrev_b32_e32 v12, 1, v145
	v_mul_f32_e32 v0, 0xc1853333, v0
	v_and_b32_e32 v10, 0xc0, v186
	v_and_b32_e32 v12, 32, v12
	v_and_b32_e32 v6, 0x118, v6
	v_mul_f32_e32 v0, v2, v0
	v_lshrrev_b32_e32 v1, 5, v144
	v_or3_b32 v10, v12, v10, v6
	v_mul_u32_u24_e32 v6, 0x600, v3
	v_max_f32_e32 v146, 0xc2700000, v0
	v_and_b32_e32 v0, 31, v145
	v_or_b32_e32 v6, v6, v7
	v_lshlrev_b32_e32 v3, 8, v3
	v_and_b32_e32 v7, 0xf0, v145
	v_lshlrev_b32_e32 v8, 8, v8
	v_lshlrev_b32_e32 v190, 4, v1
	v_bitop3_b32 v3, v11, v3, v7 bitop3:0xde
	v_bitop3_b32 v7, v11, v8, v7 bitop3:0xde
	v_lshlrev_b32_e32 v8, 8, v0
	v_and_b32_e32 v11, 0xf0, v186
	v_or_b32_e32 v12, 32, v190
	v_bitop3_b32 v16, v12, v8, v11 bitop3:0xde
	v_or_b32_e32 v12, 64, v190
	v_bitop3_b32 v17, v12, v8, v11 bitop3:0xde
	v_or_b32_e32 v12, 0x60, v190
	v_bitop3_b32 v18, v12, v8, v11 bitop3:0xde
	v_or_b32_e32 v12, 0x80, v190
	v_lshrrev_b32_e32 v2, 1, v145
	s_cmp_lg_u32 0, -1
	v_bitop3_b32 v19, v12, v8, v11 bitop3:0xde
	v_or_b32_e32 v12, 0xa0, v190
	v_and_b32_e32 v5, 0x1e0, v2
	s_cselect_b32 s0, 0, 0
	v_bitop3_b32 v20, v12, v8, v11 bitop3:0xde
	v_or_b32_e32 v12, 0xc0, v190
	v_or_b32_e32 v2, v5, v0
	v_mov_b32_e32 v149, 0
	v_add_u32_e32 v181, s0, v10
	v_bitop3_b32 v21, v12, v8, v11 bitop3:0xde
	v_or_b32_e32 v12, 0xe0, v190
	s_addk_i32 s0, 0x4000
	v_lshlrev_b32_e32 v148, 1, v6
	v_mul_u32_u24_e32 v2, 0x600, v2
	v_lshlrev_b32_e32 v4, 3, v1
	v_bitop3_b32 v15, v190, v8, v11 bitop3:0xde
	v_bitop3_b32 v11, v12, v8, v11 bitop3:0xde
	v_add_u32_e32 v191, s0, v10
	v_lshlrev_b32_e32 v8, 11, v5
	v_lshlrev_b32_e32 v10, 13, v1
	v_lshl_add_u64 v[12:13], s[72:73], 0, v[148:149]
	s_mov_b64 s[6:7], 0x14078a00
	s_mov_b64 s[92:93], s[84:85]
	v_mov_b32_e32 v147, v146
	v_mov_b32_e32 v150, v146
	v_mov_b32_e32 v151, v146
	v_mov_b32_e32 v152, v146
	v_mov_b32_e32 v153, v146
	v_mov_b32_e32 v154, v146
	v_mov_b32_e32 v155, v146
	v_mov_b32_e32 v156, v146
	v_mov_b32_e32 v157, v146
	v_mov_b32_e32 v158, v146
	v_mov_b32_e32 v159, v146
	v_mov_b32_e32 v160, v146
	v_mov_b32_e32 v161, v146
	v_mov_b32_e32 v162, v146
	v_mov_b32_e32 v163, v146
	v_cmp_gt_u32_e64 s[0:1], 32, v144
	v_lshl_add_u32 v192, v0, 2, v180
	v_add_u32_e32 v193, 0x48000, v6
	v_lshl_add_u64 v[164:165], v[12:13], 0, s[6:7]
	s_movk_i32 s3, 0x2000
	v_lshlrev_b32_e32 v166, 1, v2
	v_lshlrev_b32_e32 v168, 1, v4
	v_lshlrev_b32_e32 v170, 1, v6
	s_mov_b32 s28, 0x18000
	s_mov_b32 s29, 0x30000
	s_mov_b32 s34, 0xfffe8000
	s_mov_b64 s[6:7], 0x60000
	v_lshlrev_b32_e32 v172, 1, v8
	v_lshlrev_b32_e32 v174, 1, v10
	v_lshlrev_b32_e32 v176, 1, v0
	s_mov_b64 s[8:9], 0x1000
	s_mov_b64 s[10:11], 0x2000
	s_mov_b64 s[12:13], 0x3000
	s_movk_i32 s35, 0x3000
	s_mov_b64 s[14:15], 0x8000
	s_mov_b64 s[16:17], 0x9000
	s_mov_b32 s36, 0x9000
	s_mov_b64 s[40:41], 0xa000
	s_mov_b64 s[42:43], 0xb000
	s_mov_b32 s37, 0xb000
	s_mov_b64 s[44:45], 0x10000
	s_mov_b64 s[46:47], 0x11000
	s_mov_b32 s66, 0x11000
	s_mov_b64 s[48:49], 0x12000
	s_mov_b64 s[50:51], 0x13000
	s_mov_b32 s67, 0x13000
	s_mov_b64 s[52:53], 0x18000
	s_mov_b64 s[54:55], 0x19000
	s_mov_b32 s77, 0x19000
	s_mov_b64 s[56:57], 0x1a000
	s_mov_b64 s[58:59], 0x1b000
	s_mov_b32 s80, 0x1b000
	v_add_u32_e32 v194, 0, v14
	v_add_u32_e32 v195, 0, v9
	v_add_u32_e32 v196, 0, v3
	v_add_u32_e32 v197, 0, v7
	v_add_u32_e32 v198, 0, v15
	v_add_u32_e32 v199, 0, v16
	v_add_u32_e32 v200, 0, v17
	v_add_u32_e32 v201, 0, v18
	v_add_u32_e32 v202, 0, v19
	v_add_u32_e32 v203, 0, v20
	v_add_u32_e32 v204, 0, v21
	v_add_u32_e32 v205, 0, v11
	s_branch .LBB0_514
